# prefetch P3-P6 bf16 weight copies into cache from idle waves inside the P2->P3 grid barrier
# speedup vs baseline: 1.0603x; 1.0603x over previous
.LBB0_487:
	v_readlane_b32 s72, v251, 2
	v_readlane_b32 s73, v251, 3
	s_cmp_lt_i32 s73, 4
	v_readlane_b32 s68, v250, 14
	v_readlane_b32 s74, v251, 4
	v_readlane_b32 s75, v251, 5
	s_cbranch_scc1 .LBB0_541
	s_waitcnt vmcnt(0)
	s_barrier
	v_readfirstlane_b32 s1, v0
	s_cmp_lt_u32 s1, 64
	s_cbranch_scc1 .Lmy_touchw_skip
	v_readlane_b32 s98, v251, 20
	v_readlane_b32 s99, v251, 21
	s_mul_i32 s0, s70, 0x14000
	s_add_u32 s0, s0, 0x800000
	s_add_u32 s98, s98, s0
	s_addc_u32 s99, s99, 0
	v_add_u32_e32 v252, 0xffffffc0, v0
	v_lshlrev_b32_e32 v252, 6, v252
	s_nop 1
	global_load_dword v255, v252, s[98:99]
	v_add_u32_e32 v253, 0x7000, v252
	global_load_dword v255, v253, s[98:99]
	v_add_u32_e32 v253, 0xe000, v252
	global_load_dword v255, v253, s[98:99]
.Lmy_touchw_skip:
	s_mov_b64 s[2:3], exec
	v_readlane_b32 s0, v251, 41
	v_readlane_b32 s1, v251, 42
	s_and_b64 s[0:1], s[2:3], s[0:1]
	s_mov_b64 exec, s[0:1]
	s_cbranch_execz .LBB0_540
	s_add_i32 s0, 0, 0x22820
	v_mov_b32_e32 v2, s0
	s_waitcnt vmcnt(0) expcnt(0) lgkmcnt(0)
	ds_read_b32 v4, v2
	s_add_i32 s0, 0, 0x22824
	v_mov_b32_e32 v2, s0
	ds_read_b32 v2, v2
	s_waitcnt lgkmcnt(1)
	v_cmp_ne_u32_e32 vcc, 0, v4
	s_cbranch_vccnz .LBB0_504
	v_readlane_b32 s4, v251, 0
	v_readlane_b32 s5, v251, 1
	v_readlane_b32 s10, v251, 38
	s_load_dwordx2 s[0:1], s[4:5], 0x4
	v_readlane_b32 s11, v251, 39
	s_add_u32 s4, s10, 0x1000
	s_addc_u32 s5, s11, 0
	s_add_u32 s6, s10, 0x1100
	s_addc_u32 s7, s11, 0
	s_add_u32 s8, s10, 0x1200
	s_addc_u32 s9, s11, 0
	s_waitcnt lgkmcnt(0)
	s_mul_i32 s0, s0, s71
	s_add_u32 s10, s10, 0x1300
	s_mul_i32 s0, s0, s1
	s_addc_u32 s11, s11, 0
	s_mov_b32 s1, 1
	v_mov_b32_e32 v18, 0
	s_branch .LBB0_492

	.amdhsa_kernel _Z3fwd4Args
		.amdhsa_group_segment_fixed_size 0
		.amdhsa_private_segment_fixed_size 0
		.amdhsa_kernarg_size 464
		.amdhsa_user_sgpr_count 2
		.amdhsa_user_sgpr_dispatch_ptr 0
		.amdhsa_user_sgpr_queue_ptr 0
		.amdhsa_user_sgpr_kernarg_segment_ptr 1
		.amdhsa_user_sgpr_dispatch_id 0
		.amdhsa_user_sgpr_kernarg_preload_length 0
		.amdhsa_user_sgpr_kernarg_preload_offset 0
		.amdhsa_user_sgpr_private_segment_size 0
		.amdhsa_uses_dynamic_stack 0
		.amdhsa_enable_private_segment 0
		.amdhsa_system_sgpr_workgroup_id_x 1
		.amdhsa_system_sgpr_workgroup_id_y 0
		.amdhsa_system_sgpr_workgroup_id_z 0
		.amdhsa_system_sgpr_workgroup_info 0
		.amdhsa_system_vgpr_workitem_id 0
		.amdhsa_next_free_vgpr 256
		.amdhsa_next_free_sgpr 102
		.amdhsa_accum_offset 256
		.amdhsa_reserve_vcc 1
		.amdhsa_float_round_mode_32 0
		.amdhsa_float_round_mode_16_64 0
		.amdhsa_float_denorm_mode_32 3
		.amdhsa_float_denorm_mode_16_64 3
		.amdhsa_dx10_clamp 1
		.amdhsa_ieee_mode 1
		.amdhsa_fp16_overflow 0
		.amdhsa_tg_split 0
		.amdhsa_exception_fp_ieee_invalid_op 0
		.amdhsa_exception_fp_denorm_src 0
		.amdhsa_exception_fp_ieee_div_zero 0
		.amdhsa_exception_fp_ieee_overflow 0
		.amdhsa_exception_fp_ieee_underflow 0
		.amdhsa_exception_fp_ieee_inexact 0
		.amdhsa_exception_int_div_zero 0
	.end_amdhsa_kernel

amdhsa.kernels:
  - .agpr_count:     0
    .args:
      - .offset:         0
        .size:           208
        .value_kind:     by_value
      - .offset:         208
        .size:           4
        .value_kind:     hidden_block_count_x
      - .offset:         212
        .size:           4
        .value_kind:     hidden_block_count_y
      - .offset:         216
        .size:           4
        .value_kind:     hidden_block_count_z
      - .offset:         220
        .size:           2
        .value_kind:     hidden_group_size_x
      - .offset:         222
        .size:           2
        .value_kind:     hidden_group_size_y
      - .offset:         224
        .size:           2
        .value_kind:     hidden_group_size_z
      - .offset:         226
        .size:           2
        .value_kind:     hidden_remainder_x
      - .offset:         228
        .size:           2
        .value_kind:     hidden_remainder_y
      - .offset:         230
        .size:           2
        .value_kind:     hidden_remainder_z
      - .offset:         248
        .size:           8
        .value_kind:     hidden_global_offset_x
      - .offset:         256
        .size:           8
        .value_kind:     hidden_global_offset_y
      - .offset:         264
        .size:           8
        .value_kind:     hidden_global_offset_z
      - .offset:         272
        .size:           2
        .value_kind:     hidden_grid_dims
      - .offset:         328
        .size:           4
        .value_kind:     hidden_dynamic_lds_size
    .group_segment_fixed_size: 0
    .kernarg_segment_align: 8
    .kernarg_segment_size: 464
    .language:       OpenCL C
    .language_version:
      - 2
      - 0
    .max_flat_workgroup_size: 512
    .name:           _Z3fwd4Args
    .private_segment_fixed_size: 0
    .sgpr_count:     108
    .sgpr_spill_count: 88
    .symbol:         _Z3fwd4Args.kd
    .uniform_work_group_size: 1
    .uses_dynamic_stack: false
    .vgpr_count:     256
    .vgpr_spill_count: 0
    .wavefront_size: 64
